# scan phase: wave 0 of each block goes straight to the S5 chunk-state scan while waves 1-7 share the SSD state-scan elements (the two scans overlap instead of running back to back)
# speedup vs baseline: 1.0154x; 1.0077x over previous
.LBB0_582:
	s_andn2_b64 vcc, exec, s[0:1]
	s_mov_b64 s[2:3], 0
	s_cbranch_vccnz .LBB0_829
	v_readlane_b32 s0, v254, 53
	s_cmp_gt_i32 s0, 1
	s_mov_b64 s[0:1], -1
	s_cbranch_scc0 .LBB0_669
	v_readlane_b32 s0, v254, 53
	s_cmp_gt_i32 s0, 2
	s_mov_b64 s[0:1], -1
	s_cbranch_scc0 .LBB0_598
	s_mov_b64 s[20:21], 0
	s_mov_b32 s0, s68
	v_mov_b32_e32 v0, v181
	s_nop 0
	s_mul_i32 s0, s0, 0x1c0
	v_add_u32_e32 v1, s0, v0
	v_subrev_u32_e32 v1, 64, v1
	v_cmp_gt_u32_e32 vcc, 64, v0
	v_mov_b32_e32 v2, 0x40000
	s_nop 1
	v_cndmask_b32_e32 v1, v1, v2, vcc
	s_mov_b32 s0, 0x40000
	v_cmp_gt_i32_e32 vcc, s0, v1
	s_and_saveexec_b64 s[0:1], vcc
	s_cbranch_execz .LBB0_590
	s_add_u32 s20, s78, s20
	s_addc_u32 s21, s79, s21
	s_add_u32 s24, s20, 0x2e800000
	s_addc_u32 s25, s21, 0
	s_add_u32 s2, s78, s2
	s_addc_u32 s3, s79, s3
	s_add_u32 s38, s2, 0x6110000
	s_addc_u32 s39, s3, 0
	v_readlane_b32 s2, v254, 19
	s_mul_i32 s2, s2, 0x1c0
	s_mov_b64 s[40:41], 0
	v_readlane_b32 s3, v254, 20
